# norm tails: workgroups without a split-K extra unit take a statically assigned first chunk (no dequeue atomic at tail entry)
# speedup vs baseline: 1.0116x; 1.0047x over previous
.LBB0_727:
	s_add_u32 s0, s24, 0x44000
	v_writelane_b32 v255, s0, 2
	s_addc_u32 s0, s25, 0
	s_add_u32 s58, s24, 0x74200
	s_addc_u32 s59, s25, 0
	s_lshl_b32 s3, s91, 2
	v_add_u32_e32 v32, 64, v182
	v_cmp_lt_i32_e32 vcc, v181, v32
	s_add_u32 s44, s22, 0x4000000
	v_writelane_b32 v255, s0, 3
	v_cndmask_b32_e32 v33, v152, v181, vcc
	v_cmp_lt_i32_e32 vcc, v180, v32
	v_readlane_b32 s0, v254, 60
	s_addc_u32 s45, s23, 0
	v_lshlrev_b32_e32 v148, 2, v33
	v_cndmask_b32_e32 v33, v152, v180, vcc
	v_cmp_lt_i32_e32 vcc, v179, v32
	v_readlane_b32 s1, v254, 61
	s_add_u32 s46, s24, 0x3100000
	v_lshlrev_b32_e32 v149, 2, v33
	v_cndmask_b32_e32 v33, v152, v179, vcc
	v_cmp_lt_i32_e32 vcc, v178, v32
	v_mul_u32_u24_e32 v52, 0x10c00, v48
	v_mov_b32_e32 v53, 0
	v_lshl_add_u64 v[52:53], v[52:53], 0, s[0:1]
	s_addc_u32 s47, s25, 0
	s_add_i32 s0, s3, 0xffffc000
	v_lshlrev_b32_e32 v150, 2, v33
	v_cndmask_b32_e32 v33, v152, v178, vcc
	v_cmp_lt_i32_e32 vcc, v177, v32
	v_writelane_b32 v254, s0, 57
	s_lshr_b32 s0, s6, 4
	v_lshlrev_b32_e32 v151, 2, v33
	v_cndmask_b32_e32 v33, v152, v177, vcc
	v_cmp_lt_i32_e32 vcc, v176, v32
	s_and_b32 s0, s0, 0xfffc
	v_writelane_b32 v254, s0, 55
	v_cndmask_b32_e32 v32, v152, v176, vcc
	s_add_i32 s0, s3, -16
	v_lshlrev_b32_e32 v154, 2, v33
	v_lshlrev_b32_e32 v155, 2, v32
	v_lshlrev_b64 v[32:33], 3, v[48:49]
	v_writelane_b32 v254, s0, 53
	s_add_i32 s0, s3, 0xffffbf80
	s_add_i32 s27, 0, 0x20080
	v_cmp_gt_i32_e64 s[12:13], 16, v48
	v_lshl_add_u64 v[54:55], s[30:31], 0, v[32:33]
	v_lshl_add_u64 v[56:57], s[20:21], 0, v[32:33]
	v_lshl_add_u64 v[58:59], s[24:25], 0, v[32:33]
	v_writelane_b32 v254, s3, 58
	v_writelane_b32 v255, s0, 4
	s_mov_b32 s3, -1
	s_mov_b32 s69, 0
	v_mov_b32_e32 v61, 0
	v_mov_b32_e32 v102, 0x358637bd
	s_mov_b32 s84, 0x800000
	s_mov_b64 s[70:71], 0x800
	s_mov_b64 s[72:73], 0xa00
	s_mov_b64 s[74:75], 0xc00
	s_mov_b64 s[78:79], 0xe00
	s_mov_b64 s[42:43], 0x200
	s_mov_b64 s[28:29], 0x400
	v_mov_b32_e32 v103, 0x80
	v_mov_b32_e32 v104, s27
	s_cmp_gt_u32 s101, 47
	s_cselect_b32 s100, 1, 0
	s_sub_u32 s98, 47, s101
	v_mov_b32_e32 v253, s98
	s_mov_b32 s99, 0
	s_branch .LBB0_730

.LBB0_730:
	v_readlane_b32 s98, v254, 39
	v_readlane_b32 s99, v254, 40
	s_mov_b64 vcc, exec
	s_and_b64 exec, exec, s[98:99]
	s_cmp_eq_u32 s100, 1
	s_cbranch_scc1 .Lsfc_n1
	v_mov_b32_e32 v252, 1
	global_atomic_add v253, v61, v252, s[58:59] sc0
.Lsfc_n1:
	s_mov_b32 s100, 0
	s_mov_b64 exec, vcc
	s_mov_b32 s99, 0
	s_waitcnt vmcnt(0)
	s_barrier
	s_mov_b64 s[0:1], exec
	v_readlane_b32 s6, v254, 39
	v_readlane_b32 s7, v254, 40
	s_and_b64 s[6:7], s[0:1], s[6:7]
	s_mov_b64 exec, s[6:7]
	s_cbranch_execz .LBB0_768
	s_cmp_lt_i32 s3, 0
	s_cbranch_scc1 .LBB0_735
	s_mov_b64 s[8:9], exec
	v_mbcnt_lo_u32_b32 v32, s8, 0
	v_mbcnt_hi_u32_b32 v32, s9, v32
	v_cmp_eq_u32_e32 vcc, 0, v32
	s_and_saveexec_b64 s[6:7], vcc
	s_cbranch_execz .LBB0_734
	s_lshl_b32 s68, s3, 6
	s_lshl_b64 s[14:15], s[68:69], 2
	v_readlane_b32 s3, v255, 2
	s_add_u32 s14, s3, s14
	v_readlane_b32 s3, v255, 3
	s_addc_u32 s15, s3, s15
	s_bcnt1_i32_b64 s3, s[8:9]
	v_mov_b32_e32 v32, s3
	global_atomic_add v61, v32, s[14:15]

.LBB0_735:
	s_mov_b64 s[8:9], exec
	v_mbcnt_lo_u32_b32 v32, s8, 0
	v_mbcnt_hi_u32_b32 v32, s9, v32
	v_cmp_eq_u32_e32 vcc, 0, v32
	s_and_saveexec_b64 s[6:7], vcc
	s_cbranch_execz .LBB0_737
	s_bcnt1_i32_b64 s3, s[8:9]
	v_add_u32_e32 v33, 0xd0, v253

.LBB0_1350:
	v_mov_b32_e32 v32, v152
	v_readlane_b32 s68, v254, 4
	v_ashrrev_i32_e32 v33, 31, v32
	s_waitcnt lgkmcnt(0)
	v_lshlrev_b64 v[0:1], 4, v[32:33]
	v_readlane_b32 s70, v254, 6
	v_readlane_b32 s71, v254, 7
	s_mov_b64 s[0:1], 0x1000
	v_readlane_b32 s69, v254, 5
	v_lshl_add_u64 v[20:21], s[70:71], 0, v[0:1]
	v_lshl_add_u64 v[0:1], s[64:65], 0, v[0:1]
	v_add_co_u32_e32 v24, vcc, 0x1000, v0
	v_lshl_add_u64 v[28:29], v[0:1], 0, s[0:1]
	s_nop 0
	v_addc_co_u32_e32 v25, vcc, 0, v1, vcc
	global_load_dwordx4 v[0:3], v[20:21], off
	global_load_dwordx4 v[4:7], v[20:21], off offset:1024
	global_load_dwordx4 v[8:11], v[28:29], off offset:1024
	global_load_dwordx4 v[12:15], v[28:29], off offset:2048
	global_load_dwordx4 v[16:19], v[20:21], off offset:2048
	s_nop 0
	global_load_dwordx4 v[20:23], v[20:21], off offset:3072
	s_nop 0
	global_load_dwordx4 v[24:27], v[24:25], off
	s_nop 0
	global_load_dwordx4 v[28:31], v[28:29], off offset:3072
	s_add_u32 s0, s24, 0x5c000
	v_writelane_b32 v255, s0, 2
	s_addc_u32 s0, s25, 0
	v_writelane_b32 v255, s0, 3
	v_readlane_b32 s0, v254, 60
	v_readlane_b32 s72, v254, 8
	v_readlane_b32 s73, v254, 9
	v_readlane_b32 s74, v254, 10
	v_readlane_b32 s75, v254, 11
	v_readlane_b32 s78, v254, 14
	v_readlane_b32 s79, v254, 15
	s_add_u32 s58, s24, 0x74300
	v_readlane_b32 s1, v254, 61
	v_lshlrev_b64 v[40:41], 3, v[32:33]
	s_mov_b32 s57, 0
	s_addc_u32 s59, s25, 0
	v_cmp_gt_i32_e64 s[14:15], 16, v32
	v_mul_u32_u24_e32 v34, 0x10c00, v32
	v_mov_b32_e32 v35, 0
	v_lshl_add_u64 v[34:35], v[34:35], 0, s[0:1]
	v_lshl_add_u64 v[36:37], s[30:31], 0, v[40:41]
	v_lshl_add_u64 v[38:39], s[20:21], 0, v[40:41]
	v_lshl_add_u64 v[40:41], s[24:25], 0, v[40:41]
	s_mov_b32 s3, -1
	v_mov_b32_e32 v43, 0
	s_add_i32 s96, 0, 0x20080
	s_mov_b64 s[62:63], 0x800
	s_mov_b64 s[64:65], 0xa00
	s_mov_b64 s[68:69], 0xc00
	s_mov_b64 s[70:71], 0xe00
	v_mov_b32_e32 v146, 0x358637bd
	s_mov_b32 s97, 0x800000
	v_mov_b32_e32 v147, 0x160
	s_mov_b64 s[72:73], 0x200
	s_mov_b64 s[74:75], 0x400
	s_mov_b64 s[78:79], 0x600
	v_readlane_b32 s76, v254, 12
	v_readlane_b32 s77, v254, 13
	v_readlane_b32 s80, v254, 16
	v_readlane_b32 s81, v254, 17
	v_readlane_b32 s82, v254, 18
	v_readlane_b32 s83, v254, 19
	s_cmp_lt_u32 s101, 124
	s_cselect_b32 s100, 1, 0
	s_not_b32 s98, s101
	v_mov_b32_e32 v253, s98
	s_mov_b32 s99, 0
	s_branch .LBB0_1354

.LBB0_1354:
	v_readlane_b32 s98, v254, 39
	v_readlane_b32 s99, v254, 40
	s_mov_b64 vcc, exec
	s_and_b64 exec, exec, s[98:99]
	s_cmp_eq_u32 s100, 1
	s_cbranch_scc1 .Lsfc_n2
	v_mov_b32_e32 v252, 1
	global_atomic_add v253, v43, v252, s[58:59] sc0
.Lsfc_n2:
	s_mov_b32 s100, 0
	s_mov_b64 exec, vcc
	s_mov_b32 s99, 0
	s_waitcnt vmcnt(0)
	s_barrier
	s_mov_b64 s[0:1], exec
	v_readlane_b32 s6, v254, 39
	v_readlane_b32 s7, v254, 40
	s_and_b64 s[6:7], s[0:1], s[6:7]
	s_mov_b64 exec, s[6:7]
	s_cbranch_execz .LBB0_1392
	s_cmp_lt_i32 s3, 0
	s_cbranch_scc1 .LBB0_1359
	s_mov_b64 s[8:9], exec
	v_mbcnt_lo_u32_b32 v42, s8, 0
	v_mbcnt_hi_u32_b32 v42, s9, v42
	v_cmp_eq_u32_e32 vcc, 0, v42
	s_and_saveexec_b64 s[6:7], vcc
	s_cbranch_execz .LBB0_1358
	s_lshl_b32 s56, s3, 6
	s_lshl_b64 s[10:11], s[56:57], 2
	v_readlane_b32 s3, v255, 2
	s_add_u32 s10, s3, s10
	v_readlane_b32 s3, v255, 3
	s_addc_u32 s11, s3, s11
	s_bcnt1_i32_b64 s3, s[8:9]
	v_mov_b32_e32 v42, s3
	global_atomic_add v43, v42, s[10:11]

.LBB0_1359:
	s_mov_b64 s[8:9], exec
	v_mbcnt_lo_u32_b32 v42, s8, 0
	v_mbcnt_hi_u32_b32 v42, s9, v42
	v_cmp_eq_u32_e32 vcc, 0, v42
	s_and_saveexec_b64 s[6:7], vcc
	s_cbranch_execz .LBB0_1361
	s_bcnt1_i32_b64 s3, s[8:9]
	v_add_u32_e32 v44, 0x7c, v253

.LBB0_1963:
	v_mov_b32_e32 v32, v152
	s_mov_b64 s[0:1], 0x1000
	v_ashrrev_i32_e32 v33, 31, v32
	s_waitcnt lgkmcnt(0)
	v_lshlrev_b64 v[0:1], 4, v[32:33]
	v_lshl_add_u64 v[2:3], s[66:67], 0, v[0:1]
	v_readlane_b32 s52, v254, 4
	v_readlane_b32 s53, v254, 5
	v_lshl_add_u64 v[34:35], v[2:3], 0, s[0:1]
	v_readlane_b32 s54, v254, 6
	v_lshl_add_u64 v[4:5], s[52:53], 0, v[0:1]
	v_add_co_u32_e32 v0, vcc, 0x1000, v2
	v_lshl_add_u64 v[36:37], v[4:5], 0, s[0:1]
	s_nop 0
	v_addc_co_u32_e32 v1, vcc, 0, v3, vcc
	v_add_co_u32_e32 v4, vcc, 0x1000, v4
	global_load_dwordx4 v[0:3], v[0:1], off
	s_nop 0
	v_addc_co_u32_e32 v5, vcc, 0, v5, vcc
	global_load_dwordx4 v[4:7], v[4:5], off
	s_nop 0
	global_load_dwordx4 v[8:11], v[34:35], off offset:1024
	global_load_dwordx4 v[12:15], v[34:35], off offset:2048
	global_load_dwordx4 v[16:19], v[36:37], off offset:1024
	global_load_dwordx4 v[20:23], v[36:37], off offset:2048
	global_load_dwordx4 v[24:27], v[34:35], off offset:3072
	global_load_dwordx4 v[28:31], v[36:37], off offset:3072
	s_add_u32 s0, s24, 0x4c000
	v_readlane_b32 s55, v254, 7
	v_readlane_b32 s56, v254, 8
	v_readlane_b32 s57, v254, 9
	v_readlane_b32 s58, v254, 10
	v_readlane_b32 s59, v254, 11
	v_readlane_b32 s60, v254, 12
	v_readlane_b32 s61, v254, 13
	v_readlane_b32 s62, v254, 14
	v_readlane_b32 s63, v254, 15
	v_readlane_b32 s64, v254, 16
	v_readlane_b32 s65, v254, 17
	v_readlane_b32 s66, v254, 18
	v_readlane_b32 s67, v254, 19
	v_writelane_b32 v254, s0, 47
	s_addc_u32 s0, s25, 0
	v_writelane_b32 v255, s0, 2
	v_readlane_b32 s0, v254, 60
	s_add_u32 s36, s24, 0x74500
	v_readlane_b32 s1, v254, 61
	v_lshlrev_b64 v[40:41], 3, v[32:33]
	s_mov_b32 s15, 0
	s_addc_u32 s37, s25, 0
	v_cmp_gt_i32_e64 s[8:9], 16, v32
	v_mul_u32_u24_e32 v34, 0x10c00, v32
	v_mov_b32_e32 v35, 0
	v_lshl_add_u64 v[34:35], v[34:35], 0, s[0:1]
	v_lshl_add_u64 v[36:37], s[30:31], 0, v[40:41]
	v_lshl_add_u64 v[38:39], s[20:21], 0, v[40:41]
	v_lshl_add_u64 v[40:41], s[24:25], 0, v[40:41]
	s_mov_b32 s3, -1
	v_mov_b32_e32 v43, 0
	s_add_i32 s90, 0, 0x20080
	s_mov_b64 s[40:41], 0x800
	s_mov_b64 s[52:53], 0xa00
	s_mov_b64 s[54:55], 0xc00
	s_mov_b64 s[56:57], 0xe00
	v_mov_b32_e32 v90, 0x358637bd
	s_mov_b32 s91, 0x800000
	s_mov_b64 s[58:59], 0x200
	s_mov_b64 s[60:61], 0x400
	s_mov_b64 s[62:63], 0x600
	v_mov_b32_e32 v91, 0x80
	s_cmp_gt_u32 s101, 47
	s_cselect_b32 s100, 1, 0
	s_sub_u32 s98, 47, s101
	v_mov_b32_e32 v253, s98
	s_mov_b32 s99, 0
	s_branch .LBB0_1967

.LBB0_1967:
	v_readlane_b32 s98, v254, 39
	v_readlane_b32 s99, v254, 40
	s_mov_b64 vcc, exec
	s_and_b64 exec, exec, s[98:99]
	s_cmp_eq_u32 s100, 1
	s_cbranch_scc1 .Lsfc_n3
	v_mov_b32_e32 v252, 1
	global_atomic_add v253, v43, v252, s[36:37] sc0
.Lsfc_n3:
	s_mov_b32 s100, 0
	s_mov_b64 exec, vcc
	s_mov_b32 s99, 0
	s_waitcnt vmcnt(0)
	s_barrier
	s_mov_b64 s[0:1], exec
	v_readlane_b32 s6, v254, 39
	v_readlane_b32 s7, v254, 40
	s_and_b64 s[6:7], s[0:1], s[6:7]
	s_mov_b64 exec, s[6:7]
	s_cbranch_execz .LBB0_2005
	s_cmp_lt_i32 s3, 0
	s_cbranch_scc1 .LBB0_1972
	s_mov_b64 s[10:11], exec
	v_mbcnt_lo_u32_b32 v42, s10, 0
	v_mbcnt_hi_u32_b32 v42, s11, v42
	v_cmp_eq_u32_e32 vcc, 0, v42
	s_and_saveexec_b64 s[6:7], vcc
	s_cbranch_execz .LBB0_1971
	s_lshl_b32 s14, s3, 6
	s_lshl_b64 s[12:13], s[14:15], 2
	v_readlane_b32 s3, v254, 47
	s_add_u32 s12, s3, s12
	v_readlane_b32 s3, v255, 2
	s_addc_u32 s13, s3, s13
	s_bcnt1_i32_b64 s3, s[10:11]
	v_mov_b32_e32 v42, s3
	global_atomic_add v43, v42, s[12:13]

.LBB0_1972:
	s_mov_b64 s[10:11], exec
	v_mbcnt_lo_u32_b32 v42, s10, 0
	v_mbcnt_hi_u32_b32 v42, s11, v42
	v_cmp_eq_u32_e32 vcc, 0, v42
	s_and_saveexec_b64 s[6:7], vcc
	s_cbranch_execz .LBB0_1974
	s_bcnt1_i32_b64 s3, s[10:11]
	v_add_u32_e32 v44, 0xd0, v253

.LBB0_2391:
	v_readlane_b32 s48, v254, 4
	v_readlane_b32 s50, v254, 6
	v_ashrrev_i32_e32 v153, 31, v152
	v_readlane_b32 s51, v254, 7
	s_mov_b64 s[0:1], 0x1000
	v_readlane_b32 s55, v254, 11
	s_waitcnt lgkmcnt(0)
	v_lshl_add_u64 v[0:1], v[152:153], 4, s[50:51]
	v_lshl_add_u64 v[16:17], v[0:1], 0, s[0:1]
	v_add_co_u32_e32 v18, vcc, 0x1000, v0
	s_add_u32 s6, s24, 0x74600
	s_nop 0
	v_addc_co_u32_e32 v19, vcc, 0, v1, vcc
	global_load_dwordx4 v[0:3], v[16:17], off offset:1024
	global_load_dwordx4 v[4:7], v[16:17], off offset:2048
	global_load_dwordx4 v[8:11], v[18:19], off
	global_load_dwordx4 v[12:15], v[16:17], off offset:3072
	v_readlane_b32 s4, v254, 60
	v_readlane_b32 s54, v254, 10
	v_readlane_b32 s56, v254, 12
	v_readlane_b32 s57, v254, 13
	v_readlane_b32 s58, v254, 14
	v_readlane_b32 s59, v254, 15
	v_readlane_b32 s60, v254, 16
	v_readlane_b32 s61, v254, 17
	v_readlane_b32 s62, v254, 18
	v_readlane_b32 s63, v254, 19
	s_addc_u32 s7, s25, 0
	v_readlane_b32 s5, v254, 61
	v_lshlrev_b64 v[20:21], 3, v[152:153]
	s_add_i32 s55, 0, 0x20080
	s_mov_b32 s3, 0
	v_cmp_gt_i32_e64 s[0:1], 16, v152
	v_mul_u32_u24_e32 v16, 0x10c00, v152
	v_mov_b32_e32 v17, 0
	v_lshl_add_u64 v[16:17], v[16:17], 0, s[4:5]
	v_lshl_add_u64 v[18:19], s[20:21], 0, v[20:21]
	v_lshl_add_u64 v[20:21], s[24:25], 0, v[20:21]
	v_mov_b32_e32 v23, 0
	s_movk_i32 s33, 0x214
	s_movk_i32 s54, 0x200
	s_mov_b32 s56, 0xda00000
	s_mov_b32 s57, 0xdb80000
	s_mov_b32 s58, 0xdd00000
	s_mov_b32 s59, 0xde80000
	s_mov_b32 s60, 0xe000000
	s_mov_b32 s61, 0xe180000
	s_mov_b32 s62, 0xe300000
	s_mov_b32 s63, 0xe480000
	s_mov_b32 s64, 0xe600000
	s_mov_b32 s65, 0xe780000
	s_mov_b32 s66, 0xe900000
	v_mov_b32_e32 v122, 0x358637bd
	s_mov_b32 s67, 0x800000
	v_mov_b32_e32 v123, 0x160
	v_mov_b32_e32 v124, s55
	v_readlane_b32 s49, v254, 5
	v_readlane_b32 s52, v254, 8
	v_readlane_b32 s53, v254, 9
	s_cmp_lt_u32 s101, 124
	s_cselect_b32 s100, 1, 0
	s_not_b32 s98, s101
	v_mov_b32_e32 v253, s98
	s_mov_b32 s99, 0
	s_branch .LBB0_2395

.LBB0_2395:
	v_readlane_b32 s98, v254, 39
	v_readlane_b32 s99, v254, 40
	s_mov_b64 vcc, exec
	s_and_b64 exec, exec, s[98:99]
	s_cmp_eq_u32 s100, 1
	s_cbranch_scc1 .Lsfc_nf
	v_mov_b32_e32 v252, 1
	global_atomic_add v253, v23, v252, s[6:7] sc0
.Lsfc_nf:
	s_mov_b32 s100, 0
	s_mov_b64 exec, vcc
	s_mov_b32 s99, 0
	s_waitcnt vmcnt(0)
	s_barrier
	s_mov_b64 s[4:5], exec
	v_readlane_b32 s8, v254, 39
	v_readlane_b32 s9, v254, 40
	s_and_b64 s[8:9], s[4:5], s[8:9]
	s_mov_b64 exec, s[8:9]
	s_cbranch_execz .LBB0_2429
	s_mov_b64 s[12:13], exec
	v_mbcnt_lo_u32_b32 v22, s12, 0
	v_mbcnt_hi_u32_b32 v22, s13, v22
	v_cmp_eq_u32_e32 vcc, 0, v22
	s_and_saveexec_b64 s[8:9], vcc
	s_cbranch_execz .LBB0_2398
	s_bcnt1_i32_b64 s2, s[12:13]
	v_add_u32_e32 v24, 0x7c, v253
